# peeled first K iteration tolerates the 16 act-epilogue stores in its first two waits
# speedup vs baseline: 1.0332x; 1.0018x over previous
; #define LAS __attribute__((address_space(3)))
; __global__ void __launch_bounds__(512, 2) mega_fwd(Params p) {
;     extern __shared__ __attribute__((aligned(16))) unsigned char lds_raw[];
;     Frame F;
;     F.lds = (LAS unsigned char*)lds_raw; F.MISC = (volatile LAS unsigned*)(F.lds + LDS_MISC);
;     F.wave = __builtin_amdgcn_readfirstlane((int)threadIdx.x >> 6);
;     F.G = gridDim.x; { const int bx = blockIdx.x; F.vcu = (F.G % 8 == 0) ? (bx % 8) * (F.G / 8) + bx / 8 : bx; }
;     if (threadIdx.x < 64) F.MISC[threadIdx.x] = 0u;
_Z8mega_fwd6Params:
	s_mov_b32 s100, 0
	s_load_dword s3, s[0:1], 0xa0
	s_add_u32 s4, s0, 0xa0
	s_addc_u32 s5, s1, 0
	v_readfirstlane_b32 s34, v0
	v_writelane_b32 v243, s4, 0
	s_waitcnt lgkmcnt(0)
	s_mov_b32 s8, s3
	s_and_b32 s3, s3, 7
	s_cmp_lg_u32 s3, 0
	s_mov_b32 s60, s2
	s_mov_b32 s3, s2
	v_writelane_b32 v243, s5, 1
	s_cbranch_scc0 .LBB0_29
	s_load_dwordx2 s[64:65], s[0:1], 0x98
	v_cmp_gt_u32_e32 vcc, 64, v0
	s_and_saveexec_b64 s[4:5], vcc

; #define GAS __attribute__((address_space(1)))
;     __device__ __forceinline__ GAS float* outp() const { return (GAS float*)rd(17); }
;     __device__ __forceinline__ GAS unsigned char* wsp() const { return (GAS unsigned char*)rd(18); }
; #define F_qng F.in(9)
; __global__ void __launch_bounds__(512, 2) mega_fwd(Params p) {
;     ...
;         if (IN(pb + 1)) { pg8::Gemm g{(const GAS bf16*)(F.wsp() + WS_XN), (const GAS bf16*)(F.wsp() + WS_WIN) + (size_t)l * NPROJ * D, 0, 0, MTOT / 256, NPROJ / 256, 1, D, 0, WGM_PROJ};
;             pg8::Order S; S.init(g, F.G, (int)blockIdx.x);
;             pg8::EpiProj E{l, F.wsp(), F.outp(), F_qng + l * 128, F_kng + l * 128, (const GAS float*)(F.wsp() + WS_LB) + l * 1024};
;             pg8::gemm_phase(F.lds, g, S, E, F.wave);
.LBB0_172:
	s_mov_b32 s100, 0
	v_readlane_b32 s8, v240, 7
	s_add_i32 s12, s8, 2
	s_cmp_le_i32 s64, s12
	s_cselect_b64 s[8:9], -1, 0
	s_cmp_lt_i32 s12, s65
	s_cselect_b64 s[12:13], -1, 0
	s_and_b64 s[12:13], s[8:9], s[12:13]
	s_mov_b64 s[8:9], -1
	s_and_b64 vcc, exec, s[12:13]
	s_cbranch_vccnz .LBB0_174
	v_readlane_b32 s8, v240, 7
	s_add_i32 s12, s8, 3
	s_mov_b64 s[8:9], 0

; #define GAS __attribute__((address_space(1)))
; #define PG8_STAGE(bufoff, gbase, voff) do { _Pragma("unroll") for (int _i = 0; _i < 2; ++_i) \
;         __builtin_amdgcn_global_load_lds((const GAS unsigned*)((const GAS char*)(gbase) + (voff)[_i]), (LAS unsigned*)(lds + (bufoff) + ldsw + _i * 8192), 16, 0, 0); } while (0)
; #define PG8_LDA(dst, b, h) do { _Pragma("unroll") for (int m = 0; m < 4; ++m) _Pragma("unroll") for (int k = 0; k < 2; ++k) dst[m][k] = *(const LAS bf16x8*)(lds + PG8_SA(b, h) + aoff + m * 2048 + k * 1024); } while (0)
; #define PG8_LDB(dst, b, h) do { _Pragma("unroll") for (int n = 0; n < 2; ++n) _Pragma("unroll") for (int k = 0; k < 2; ++k) dst[n][k] = *(const LAS bf16x8*)(lds + PG8_SB(b, h) + boff + n * 2048 + k * 1024); } while (0)
; #define PG8_MMA(ai, bj, At, Bt) do { __builtin_amdgcn_s_setprio(1); _Pragma("unroll") for (int m = 0; m < 4; ++m) _Pragma("unroll") for (int n = 0; n < 2; ++n) _Pragma("unroll") for (int k = 0; k < 2; ++k) \
;         acc[ai][bj][m][n] = __builtin_amdgcn_mfma_f32_16x16x32_bf16(Bt[n][k], At[m][k], acc[ai][bj][m][n], 0, 0, 0); __builtin_amdgcn_s_setprio(0); } while (0)
; #define PG8_WAIT_V(n) asm volatile("s_waitcnt vmcnt(" #n ")" ::: "memory")
;     ...
;         const GAS char* nA = has_next ? (const GAS char*)(g.A + (size_t)nxt.seg * g.a_seg) + (size_t)nxt.pm * tstep + (MODE ? (size_t)nxt.k0 * kstep : 0) : cA; const GAS char* nB = has_next ? (const GAS char*)(g.Bt + (size_t)nxt.seg * g.b_seg) + (size_t)nxt.pn * tstep + (MODE ? (size_t)nxt.k0 * kstep : 0) : cB;
;         const int nt = MODE == 0 ? K / BK : cur.nk;
;         for (int t = 0; t < nt; t += 2) {
;             const bool last = (t == nt - 2);
;             const GAS char* a1 = cA + (size_t)(t + 1) * kstep;
;             const GAS char* a2 = last ? nA : cA + (size_t)(t + 2) * kstep; const GAS char* b2 = last ? nB : cB + (size_t)(t + 2) * kstep;
;             const GAS char* a3 = a2 + kstep; const GAS char* b3 = b2 + kstep;
;             PG8_LDB(B0, 0, 0); PG8_LDB(B1, 0, 1); PG8_SCHED; PG8_LDA(At, 0, 0); PG8_STAGE(PG8_SA(1, 1), a1 + hstep, voffA);
;             PG8_WAIT_V(8); PG8_WAIT_L(0); PG8_BAR; PG8_MMA(0, 0, At, B0); PG8_MMA(0, 1, At, B1); PG8_BAR; PG8_SCHED;
;             PG8_LDA(At, 0, 1); PG8_STAGE(PG8_SB(0, 0), b2, voffB); PG8_STAGE(PG8_SB(0, 1), b2 + hstep, voffB); PG8_STAGE(PG8_SA(0, 0), a2, voffA);
.LBB0_189:
	s_ashr_i32 s89, s88, 31
	s_lshl_b64 s[8:9], s[88:89], 19
	s_add_u32 s8, s13, s8
	s_addc_u32 s9, s14, s9
	s_and_b64 s[26:27], s[60:61], exec
	s_cselect_b32 s17, s9, s37
	s_cselect_b32 s20, s8, s36
	s_ashr_i32 s93, s92, 31
	s_lshl_b64 s[26:27], s[92:93], 19
	s_add_u32 s26, s15, s26
	s_addc_u32 s27, s68, s27
	s_and_b64 s[52:53], s[60:61], exec
	s_cselect_b32 s25, s27, s35
	s_cselect_b32 s62, s26, s34
	s_add_u32 s63, s34, 0x100
	s_addc_u32 s64, s35, 0
	s_add_u32 s34, s36, 0x40080
	s_addc_u32 s35, s37, 0
	s_mov_b32 s65, -2
	s_add_u32 s36, s34, 0xfffc0080
	s_addc_u32 s37, s35, -1
	s_add_i32 s75, 0, 0x10000
	s_cmp_eq_u32 s65, 12
	s_cselect_b32 s53, s17, s37
	s_cselect_b32 s52, s20, s36
	s_cselect_b32 s37, s25, s64
	s_cselect_b32 s36, s62, s63
	s_add_i32 s89, 0, 0x14000
	v_add_u32_e32 v156, s75, v218
	v_add_u32_e32 v172, s89, v218
	ds_read_b128 v[128:131], v156
	ds_read_b128 v[132:135], v156 offset:1024
	ds_read_b128 v[152:155], v156 offset:2048
	ds_read_b128 v[156:159], v156 offset:3072
	ds_read_b128 v[160:163], v172
	ds_read_b128 v[164:167], v172 offset:1024
	ds_read_b128 v[168:171], v172 offset:2048
	ds_read_b128 v[182:185], v172 offset:3072
	v_lshl_add_u64 v[230:231], s[34:35], 0, v[150:151]
	s_add_i32 m0, s56, 0xc000
	ds_read_b128 v[186:189], v220
	ds_read_b128 v[190:193], v220 offset:1024
	ds_read_b128 v[194:197], v220 offset:2048
	ds_read_b128 v[198:201], v220 offset:3072
	ds_read_b128 v[202:205], v220 offset:4096
	ds_read_b128 v[206:209], v220 offset:5120
	ds_read_b128 v[222:225], v220 offset:6144
	ds_read_b128 v[226:229], v220 offset:7168
	global_load_lds_dwordx4 v[230:231], off
	v_lshl_add_u64 v[230:231], s[34:35], 0, v[148:149]
	s_add_i32 m0, s56, 0xe000
	s_nop 0
	global_load_lds_dwordx4 v[230:231], off
	s_cmp_lg_u32 s100, 0
	s_cbranch_scc1 .Lrx1a
	s_waitcnt vmcnt(8)
	s_branch .Lrx1b
.Lrx1a:
	s_waitcnt vmcnt(24)
.Lrx1b:
	s_waitcnt lgkmcnt(0)
	s_barrier
	s_setprio 1
	s_waitcnt lgkmcnt(0)
	v_mfma_f32_16x16x32_bf16 v[124:127], v[128:131], v[186:189], 0
	v_mfma_f32_16x16x32_bf16 v[120:123], v[152:155], v[186:189], 0
	v_mfma_f32_16x16x32_bf16 v[108:111], v[128:131], v[194:197], 0
	v_mfma_f32_16x16x32_bf16 v[104:107], v[152:155], v[194:197], 0
	v_mfma_f32_16x16x32_bf16 v[92:95], v[128:131], v[202:205], 0
	v_mfma_f32_16x16x32_bf16 v[88:91], v[152:155], v[202:205], 0
	v_mfma_f32_16x16x32_bf16 v[76:79], v[128:131], v[222:225], 0
	v_mfma_f32_16x16x32_bf16 v[72:75], v[152:155], v[222:225], 0
	v_mfma_f32_16x16x32_bf16 v[124:127], v[132:135], v[190:193], v[124:127]
	v_mfma_f32_16x16x32_bf16 v[120:123], v[156:159], v[190:193], v[120:123]
	v_mfma_f32_16x16x32_bf16 v[108:111], v[132:135], v[198:201], v[108:111]
	v_mfma_f32_16x16x32_bf16 v[104:107], v[156:159], v[198:201], v[104:107]
	v_mfma_f32_16x16x32_bf16 v[92:95], v[132:135], v[206:209], v[92:95]
	v_mfma_f32_16x16x32_bf16 v[88:91], v[156:159], v[206:209], v[88:91]
	v_mfma_f32_16x16x32_bf16 v[76:79], v[132:135], v[226:229], v[76:79]
	v_mfma_f32_16x16x32_bf16 v[72:75], v[156:159], v[226:229], v[72:75]
	s_setprio 0
	s_setprio 1
	v_mfma_f32_16x16x32_bf16 v[116:119], v[160:163], v[186:189], 0
	v_mfma_f32_16x16x32_bf16 v[112:115], v[168:171], v[186:189], 0
	v_mfma_f32_16x16x32_bf16 v[100:103], v[160:163], v[194:197], 0
	v_mfma_f32_16x16x32_bf16 v[96:99], v[168:171], v[194:197], 0
	v_mfma_f32_16x16x32_bf16 v[84:87], v[160:163], v[202:205], 0
	v_mfma_f32_16x16x32_bf16 v[80:83], v[168:171], v[202:205], 0
	v_mfma_f32_16x16x32_bf16 v[68:71], v[160:163], v[222:225], 0
	v_mfma_f32_16x16x32_bf16 v[64:67], v[168:171], v[222:225], 0
	v_mfma_f32_16x16x32_bf16 v[116:119], v[164:167], v[190:193], v[116:119]
	v_mfma_f32_16x16x32_bf16 v[112:115], v[182:185], v[190:193], v[112:115]
	v_mfma_f32_16x16x32_bf16 v[100:103], v[164:167], v[198:201], v[100:103]
	v_mfma_f32_16x16x32_bf16 v[96:99], v[182:185], v[198:201], v[96:99]
	v_mfma_f32_16x16x32_bf16 v[84:87], v[164:167], v[206:209], v[84:87]
	v_mfma_f32_16x16x32_bf16 v[80:83], v[182:185], v[206:209], v[80:83]
	v_mfma_f32_16x16x32_bf16 v[68:71], v[164:167], v[226:229], v[68:71]
	v_mfma_f32_16x16x32_bf16 v[64:67], v[182:185], v[226:229], v[64:67]
	s_setprio 0
	s_barrier
	s_add_i32 s75, s75, s95
	v_lshl_add_u64 v[230:231], s[36:37], 0, v[138:139]
	s_mov_b32 m0, s75
	ds_read_b128 v[186:189], v220 offset:16384
	ds_read_b128 v[190:193], v220 offset:17408
	ds_read_b128 v[194:197], v220 offset:18432
	ds_read_b128 v[198:201], v220 offset:19456
	ds_read_b128 v[202:205], v220 offset:20480
	ds_read_b128 v[206:209], v220 offset:21504
	ds_read_b128 v[222:225], v220 offset:22528
	ds_read_b128 v[226:229], v220 offset:23552
	global_load_lds_dwordx4 v[230:231], off
	s_add_i32 m0, s75, 0x2000
	s_add_u32 s90, s36, 0x40000
	v_lshl_add_u64 v[232:233], s[36:37], 0, v[142:143]
	s_addc_u32 s91, s37, 0
	s_add_i32 s75, s89, s95
	global_load_lds_dwordx4 v[232:233], off
	v_lshl_add_u64 v[234:235], s[90:91], 0, v[138:139]
	s_mov_b32 m0, s75
	v_lshl_add_u64 v[236:237], s[52:53], 0, v[140:141]
	global_load_lds_dwordx4 v[234:235], off
	v_lshl_add_u64 v[234:235], s[90:91], 0, v[142:143]
	s_add_i32 m0, s75, 0x2000
	s_nop 0
	global_load_lds_dwordx4 v[234:235], off
	v_lshl_add_u64 v[234:235], s[52:53], 0, v[136:137]
	s_mov_b32 m0, s56
	s_nop 0
	global_load_lds_dwordx4 v[234:235], off
	s_mov_b32 m0, s57
	s_nop 0
	global_load_lds_dwordx4 v[236:237], off
	s_cmp_lg_u32 s100, 0
	s_cbranch_scc1 .Lrx2a
	s_waitcnt vmcnt(8)
	s_branch .Lrx2b

; #define PG8_STAGE(bufoff, gbase, voff) do { _Pragma("unroll") for (int _i = 0; _i < 2; ++_i) \
;         __builtin_amdgcn_global_load_lds((const GAS unsigned*)((const GAS char*)(gbase) + (voff)[_i]), (LAS unsigned*)(lds + (bufoff) + ldsw + _i * 8192), 16, 0, 0); } while (0)
; #define PG8_LDA(dst, b, h) do { _Pragma("unroll") for (int m = 0; m < 4; ++m) _Pragma("unroll") for (int k = 0; k < 2; ++k) dst[m][k] = *(const LAS bf16x8*)(lds + PG8_SA(b, h) + aoff + m * 2048 + k * 1024); } while (0)
; #define PG8_LDB(dst, b, h) do { _Pragma("unroll") for (int n = 0; n < 2; ++n) _Pragma("unroll") for (int k = 0; k < 2; ++k) dst[n][k] = *(const LAS bf16x8*)(lds + PG8_SB(b, h) + boff + n * 2048 + k * 1024); } while (0)
; #define PG8_MMA(ai, bj, At, Bt) do { __builtin_amdgcn_s_setprio(1); _Pragma("unroll") for (int m = 0; m < 4; ++m) _Pragma("unroll") for (int n = 0; n < 2; ++n) _Pragma("unroll") for (int k = 0; k < 2; ++k) \
;         acc[ai][bj][m][n] = __builtin_amdgcn_mfma_f32_16x16x32_bf16(Bt[n][k], At[m][k], acc[ai][bj][m][n], 0, 0, 0); __builtin_amdgcn_s_setprio(0); } while (0)
; #define PG8_WAIT_V(n) asm volatile("s_waitcnt vmcnt(" #n ")" ::: "memory")
; #define PG8_WAIT_L(n) asm volatile("s_waitcnt lgkmcnt(" #n ")" ::: "memory")
; #define PG8_BAR __builtin_amdgcn_s_barrier()
; #define PG8_SCHED __builtin_amdgcn_sched_barrier(0)
;     ...
;             PG8_WAIT_V(8); PG8_WAIT_L(0); PG8_BAR; PG8_MMA(1, 0, At, B0); PG8_MMA(1, 1, At, B1); PG8_BAR; PG8_SCHED;
;             PG8_LDB(B0, 1, 0); PG8_LDB(B1, 1, 1); PG8_SCHED; PG8_LDA(At, 1, 0); PG8_STAGE(PG8_SA(0, 1), a2 + hstep, voffA);
;             PG8_WAIT_V(8); PG8_WAIT_L(0); PG8_BAR; PG8_MMA(0, 0, At, B0); PG8_MMA(0, 1, At, B1); PG8_BAR; PG8_SCHED;
.Lrx2b:
	s_mov_b32 s100, 0
	s_waitcnt lgkmcnt(0)
	s_barrier
	s_setprio 1
	s_waitcnt lgkmcnt(0)
	v_mfma_f32_16x16x32_bf16 v[60:63], v[128:131], v[186:189], 0
	v_mfma_f32_16x16x32_bf16 v[56:59], v[152:155], v[186:189], 0
	v_mfma_f32_16x16x32_bf16 v[44:47], v[128:131], v[194:197], 0
	v_mfma_f32_16x16x32_bf16 v[40:43], v[152:155], v[194:197], 0
	v_mfma_f32_16x16x32_bf16 v[28:31], v[128:131], v[202:205], 0
	v_mfma_f32_16x16x32_bf16 v[24:27], v[152:155], v[202:205], 0
	v_mfma_f32_16x16x32_bf16 v[12:15], v[128:131], v[222:225], 0
	v_mfma_f32_16x16x32_bf16 v[8:11], v[152:155], v[222:225], 0
	v_mfma_f32_16x16x32_bf16 v[60:63], v[132:135], v[190:193], v[60:63]
	v_mfma_f32_16x16x32_bf16 v[56:59], v[156:159], v[190:193], v[56:59]
	v_mfma_f32_16x16x32_bf16 v[44:47], v[132:135], v[198:201], v[44:47]
	v_mfma_f32_16x16x32_bf16 v[40:43], v[156:159], v[198:201], v[40:43]
	v_mfma_f32_16x16x32_bf16 v[28:31], v[132:135], v[206:209], v[28:31]
	v_mfma_f32_16x16x32_bf16 v[24:27], v[156:159], v[206:209], v[24:27]
	v_mfma_f32_16x16x32_bf16 v[12:15], v[132:135], v[226:229], v[12:15]
	v_mfma_f32_16x16x32_bf16 v[8:11], v[156:159], v[226:229], v[8:11]
	s_setprio 0
	s_setprio 1
	v_mfma_f32_16x16x32_bf16 v[52:55], v[160:163], v[186:189], 0
	v_mfma_f32_16x16x32_bf16 v[48:51], v[168:171], v[186:189], 0
	v_mfma_f32_16x16x32_bf16 v[36:39], v[160:163], v[194:197], 0
	v_mfma_f32_16x16x32_bf16 v[32:35], v[168:171], v[194:197], 0
	v_mfma_f32_16x16x32_bf16 v[20:23], v[160:163], v[202:205], 0
	v_mfma_f32_16x16x32_bf16 v[16:19], v[168:171], v[202:205], 0
	v_mfma_f32_16x16x32_bf16 v[4:7], v[160:163], v[222:225], 0
	v_mfma_f32_16x16x32_bf16 v[0:3], v[168:171], v[222:225], 0
	v_mfma_f32_16x16x32_bf16 v[52:55], v[164:167], v[190:193], v[52:55]
	v_mfma_f32_16x16x32_bf16 v[48:51], v[182:185], v[190:193], v[48:51]
	v_mfma_f32_16x16x32_bf16 v[36:39], v[164:167], v[198:201], v[36:39]
	v_mfma_f32_16x16x32_bf16 v[32:35], v[182:185], v[198:201], v[32:35]
	v_mfma_f32_16x16x32_bf16 v[20:23], v[164:167], v[206:209], v[20:23]
	v_mfma_f32_16x16x32_bf16 v[16:19], v[182:185], v[206:209], v[16:19]
	v_mfma_f32_16x16x32_bf16 v[4:7], v[164:167], v[226:229], v[4:7]
	v_mfma_f32_16x16x32_bf16 v[0:3], v[182:185], v[226:229], v[0:3]
	s_setprio 0
	s_barrier
	s_add_i32 s75, 0, 0x18000
	s_add_i32 s89, 0, 0x1c000
	v_add_u32_e32 v156, s75, v218
	v_add_u32_e32 v172, s89, v218
	ds_read_b128 v[128:131], v156
	ds_read_b128 v[132:135], v156 offset:1024
	ds_read_b128 v[152:155], v156 offset:2048
	ds_read_b128 v[156:159], v156 offset:3072
	ds_read_b128 v[160:163], v172
	ds_read_b128 v[164:167], v172 offset:1024
	ds_read_b128 v[168:171], v172 offset:2048
	ds_read_b128 v[182:185], v172 offset:3072
	s_add_u32 s52, s52, 0x40000
	s_addc_u32 s53, s53, 0
	s_mov_b32 m0, s69
	v_lshl_add_u64 v[238:239], s[52:53], 0, v[136:137]
	ds_read_b128 v[186:189], v220 offset:32768
	ds_read_b128 v[190:193], v220 offset:33792
	ds_read_b128 v[194:197], v220 offset:34816
	ds_read_b128 v[198:201], v220 offset:35840
	ds_read_b128 v[202:205], v220 offset:36864
	ds_read_b128 v[206:209], v220 offset:37888
	ds_read_b128 v[222:225], v220 offset:38912
	ds_read_b128 v[226:229], v220 offset:39936
	global_load_lds_dwordx4 v[238:239], off
	v_lshl_add_u64 v[238:239], s[52:53], 0, v[140:141]
	s_mov_b32 m0, s66
	s_nop 0
	global_load_lds_dwordx4 v[238:239], off
	s_waitcnt vmcnt(8)
	s_waitcnt lgkmcnt(0)
	s_barrier
	s_setprio 1
	s_waitcnt lgkmcnt(0)
	v_mfma_f32_16x16x32_bf16 v[124:127], v[128:131], v[186:189], v[124:127]
	v_mfma_f32_16x16x32_bf16 v[120:123], v[152:155], v[186:189], v[120:123]
	v_mfma_f32_16x16x32_bf16 v[108:111], v[128:131], v[194:197], v[108:111]
	v_mfma_f32_16x16x32_bf16 v[104:107], v[152:155], v[194:197], v[104:107]
	v_mfma_f32_16x16x32_bf16 v[92:95], v[128:131], v[202:205], v[92:95]
	v_mfma_f32_16x16x32_bf16 v[88:91], v[152:155], v[202:205], v[88:91]
	v_mfma_f32_16x16x32_bf16 v[76:79], v[128:131], v[222:225], v[76:79]
	v_mfma_f32_16x16x32_bf16 v[72:75], v[152:155], v[222:225], v[72:75]
	v_mfma_f32_16x16x32_bf16 v[124:127], v[132:135], v[190:193], v[124:127]
	v_mfma_f32_16x16x32_bf16 v[120:123], v[156:159], v[190:193], v[120:123]
	v_mfma_f32_16x16x32_bf16 v[108:111], v[132:135], v[198:201], v[108:111]
	v_mfma_f32_16x16x32_bf16 v[104:107], v[156:159], v[198:201], v[104:107]
	v_mfma_f32_16x16x32_bf16 v[92:95], v[132:135], v[206:209], v[92:95]
	v_mfma_f32_16x16x32_bf16 v[88:91], v[156:159], v[206:209], v[88:91]
	v_mfma_f32_16x16x32_bf16 v[76:79], v[132:135], v[226:229], v[76:79]
	v_mfma_f32_16x16x32_bf16 v[72:75], v[156:159], v[226:229], v[72:75]
	s_setprio 0
	s_setprio 1
	v_mfma_f32_16x16x32_bf16 v[116:119], v[160:163], v[186:189], v[116:119]
	v_mfma_f32_16x16x32_bf16 v[112:115], v[168:171], v[186:189], v[112:115]
	v_mfma_f32_16x16x32_bf16 v[100:103], v[160:163], v[194:197], v[100:103]
	v_mfma_f32_16x16x32_bf16 v[96:99], v[168:171], v[194:197], v[96:99]
	v_mfma_f32_16x16x32_bf16 v[84:87], v[160:163], v[202:205], v[84:87]
	v_mfma_f32_16x16x32_bf16 v[80:83], v[168:171], v[202:205], v[80:83]
	v_mfma_f32_16x16x32_bf16 v[68:71], v[160:163], v[222:225], v[68:71]
	v_mfma_f32_16x16x32_bf16 v[64:67], v[168:171], v[222:225], v[64:67]
	v_mfma_f32_16x16x32_bf16 v[116:119], v[164:167], v[190:193], v[116:119]
	v_mfma_f32_16x16x32_bf16 v[112:115], v[182:185], v[190:193], v[112:115]
	v_mfma_f32_16x16x32_bf16 v[100:103], v[164:167], v[198:201], v[100:103]
	v_mfma_f32_16x16x32_bf16 v[96:99], v[182:185], v[198:201], v[96:99]
	v_mfma_f32_16x16x32_bf16 v[84:87], v[164:167], v[206:209], v[84:87]
	v_mfma_f32_16x16x32_bf16 v[80:83], v[182:185], v[206:209], v[80:83]
	v_mfma_f32_16x16x32_bf16 v[68:71], v[164:167], v[226:229], v[68:71]
	v_mfma_f32_16x16x32_bf16 v[64:67], v[182:185], v[226:229], v[64:67]
	s_setprio 0
	s_barrier
; #define PG8_STAGE(bufoff, gbase, voff) do { _Pragma("unroll") for (int _i = 0; _i < 2; ++_i) \
;         __builtin_amdgcn_global_load_lds((const GAS unsigned*)((const GAS char*)(gbase) + (voff)[_i]), (LAS unsigned*)(lds + (bufoff) + ldsw + _i * 8192), 16, 0, 0); } while (0)
; #define PG8_LDA(dst, b, h) do { _Pragma("unroll") for (int m = 0; m < 4; ++m) _Pragma("unroll") for (int k = 0; k < 2; ++k) dst[m][k] = *(const LAS bf16x8*)(lds + PG8_SA(b, h) + aoff + m * 2048 + k * 1024); } while (0)
; #define PG8_MMA(ai, bj, At, Bt) do { __builtin_amdgcn_s_setprio(1); _Pragma("unroll") for (int m = 0; m < 4; ++m) _Pragma("unroll") for (int n = 0; n < 2; ++n) _Pragma("unroll") for (int k = 0; k < 2; ++k) \
;         acc[ai][bj][m][n] = __builtin_amdgcn_mfma_f32_16x16x32_bf16(Bt[n][k], At[m][k], acc[ai][bj][m][n], 0, 0, 0); __builtin_amdgcn_s_setprio(0); } while (0)
; #define PG8_WAIT_V(n) asm volatile("s_waitcnt vmcnt(" #n ")" ::: "memory")
; #define PG8_WAIT_L(n) asm volatile("s_waitcnt lgkmcnt(" #n ")" ::: "memory")
; #define PG8_BAR __builtin_amdgcn_s_barrier()
; #define PG8_SCHED __builtin_amdgcn_sched_barrier(0)
;     ...
;             PG8_LDA(At, 1, 1); PG8_STAGE(PG8_SB(1, 0), b3, voffB); PG8_STAGE(PG8_SB(1, 1), b3 + hstep, voffB); PG8_STAGE(PG8_SA(1, 0), a3, voffA);
;             PG8_WAIT_V(8); PG8_WAIT_L(0); PG8_BAR; PG8_MMA(1, 0, At, B0); PG8_MMA(1, 1, At, B1); PG8_BAR; PG8_SCHED;
	s_add_i32 s52, s75, s95
	v_lshl_add_u64 v[230:231], v[230:231], 0, s[82:83]
	s_mov_b32 m0, s52
	ds_read_b128 v[186:189], v220 offset:49152
	ds_read_b128 v[190:193], v220 offset:50176
	ds_read_b128 v[194:197], v220 offset:51200
	ds_read_b128 v[198:201], v220 offset:52224
	ds_read_b128 v[202:205], v220 offset:53248
	ds_read_b128 v[206:209], v220 offset:54272
	ds_read_b128 v[222:225], v220 offset:55296
	ds_read_b128 v[226:229], v220 offset:56320
	global_load_lds_dwordx4 v[230:231], off
	s_add_i32 m0, s52, 0x2000
	s_add_u32 s36, s36, 0x40080
	v_lshl_add_u64 v[230:231], v[232:233], 0, s[82:83]
	s_addc_u32 s37, s37, 0
	s_add_i32 s52, s89, s95
	global_load_lds_dwordx4 v[230:231], off
	v_lshl_add_u64 v[230:231], s[36:37], 0, v[138:139]
	s_mov_b32 m0, s52
	s_nop 0
	global_load_lds_dwordx4 v[230:231], off
	v_lshl_add_u64 v[230:231], s[36:37], 0, v[142:143]
	s_add_i32 m0, s52, 0x2000
	s_nop 0
	global_load_lds_dwordx4 v[230:231], off
	v_lshl_add_u64 v[230:231], v[234:235], 0, s[82:83]
	s_mov_b32 m0, s67
	s_nop 0
	global_load_lds_dwordx4 v[230:231], off
	v_lshl_add_u64 v[230:231], v[236:237], 0, s[82:83]
	s_mov_b32 m0, s12
	s_nop 0
	global_load_lds_dwordx4 v[230:231], off
	s_waitcnt vmcnt(8)
	s_waitcnt lgkmcnt(0)
	s_barrier
	s_setprio 1
	s_waitcnt lgkmcnt(0)
	v_mfma_f32_16x16x32_bf16 v[60:63], v[128:131], v[186:189], v[60:63]
	v_mfma_f32_16x16x32_bf16 v[56:59], v[152:155], v[186:189], v[56:59]
	v_mfma_f32_16x16x32_bf16 v[44:47], v[128:131], v[194:197], v[44:47]
	v_mfma_f32_16x16x32_bf16 v[40:43], v[152:155], v[194:197], v[40:43]
	v_mfma_f32_16x16x32_bf16 v[28:31], v[128:131], v[202:205], v[28:31]
	v_mfma_f32_16x16x32_bf16 v[24:27], v[152:155], v[202:205], v[24:27]
	v_mfma_f32_16x16x32_bf16 v[12:15], v[128:131], v[222:225], v[12:15]
	v_mfma_f32_16x16x32_bf16 v[8:11], v[152:155], v[222:225], v[8:11]
	v_mfma_f32_16x16x32_bf16 v[60:63], v[132:135], v[190:193], v[60:63]
	v_mfma_f32_16x16x32_bf16 v[56:59], v[156:159], v[190:193], v[56:59]
	v_mfma_f32_16x16x32_bf16 v[44:47], v[132:135], v[198:201], v[44:47]
	v_mfma_f32_16x16x32_bf16 v[40:43], v[156:159], v[198:201], v[40:43]
	v_mfma_f32_16x16x32_bf16 v[28:31], v[132:135], v[206:209], v[28:31]
	v_mfma_f32_16x16x32_bf16 v[24:27], v[156:159], v[206:209], v[24:27]
	v_mfma_f32_16x16x32_bf16 v[12:15], v[132:135], v[226:229], v[12:15]
	v_mfma_f32_16x16x32_bf16 v[8:11], v[156:159], v[226:229], v[8:11]
	s_setprio 0
	s_setprio 1
	v_mfma_f32_16x16x32_bf16 v[52:55], v[160:163], v[186:189], v[52:55]
	v_mfma_f32_16x16x32_bf16 v[48:51], v[168:171], v[186:189], v[48:51]
	v_mfma_f32_16x16x32_bf16 v[36:39], v[160:163], v[194:197], v[36:39]
	v_mfma_f32_16x16x32_bf16 v[32:35], v[168:171], v[194:197], v[32:35]
	v_mfma_f32_16x16x32_bf16 v[20:23], v[160:163], v[202:205], v[20:23]
	v_mfma_f32_16x16x32_bf16 v[16:19], v[168:171], v[202:205], v[16:19]
	v_mfma_f32_16x16x32_bf16 v[4:7], v[160:163], v[222:225], v[4:7]
	v_mfma_f32_16x16x32_bf16 v[0:3], v[168:171], v[222:225], v[0:3]
	v_mfma_f32_16x16x32_bf16 v[52:55], v[164:167], v[190:193], v[52:55]
	v_mfma_f32_16x16x32_bf16 v[48:51], v[182:185], v[190:193], v[48:51]
	v_mfma_f32_16x16x32_bf16 v[36:39], v[164:167], v[198:201], v[36:39]
	v_mfma_f32_16x16x32_bf16 v[32:35], v[182:185], v[198:201], v[32:35]
	v_mfma_f32_16x16x32_bf16 v[20:23], v[164:167], v[206:209], v[20:23]
	v_mfma_f32_16x16x32_bf16 v[16:19], v[182:185], v[206:209], v[16:19]
	v_mfma_f32_16x16x32_bf16 v[4:7], v[164:167], v[226:229], v[4:7]
	v_mfma_f32_16x16x32_bf16 v[0:3], v[182:185], v[226:229], v[0:3]
	s_setprio 0
	s_barrier
	s_add_i32 s65, s65, 2
	s_add_u32 s63, s63, 0x100
	s_addc_u32 s64, s64, 0
	s_add_u32 s34, s34, 0x100
	s_addc_u32 s35, s35, 0

; #define GAS __attribute__((address_space(1)))
; #define EPI_FOR_ROWS for (int ai = 0; ai < 2; ++ai) _Pragma("unroll") for (int m = 0; m < 4; ++m)
; #define NT_ST(p, v) __builtin_nontemporal_store((v), (p))
;     __device__ __forceinline__ void operator()(Acc& acc, const Unit& u, int wr, int wc, int fr, int fq, LAS unsigned char* lds) const {
;     ...
;         if (grp == 0) {
; #pragma unroll
;             EPI_FOR_ROWS { const int row = row0 + ai * 128 + m * 16; GAS float* d = nullptr;
;                 if (sample) { const int rr = row - MPAD, b = rr >> 6, i = rr & 63; if (i >= DSEQ - 15) d = out + O_PS + (((size_t)layer * DBATCH + b) * 15 + (i - (DSEQ - 15))) * 1024; }
;                 else if (row < MP) { const int b = row / LP, t = row - b * LP; if (t >= LP - 15) d = out + O_PP + (((size_t)layer * BATCH + b) * 15 + (t - (LP - 15))) * 1024; }
;                 if (d) {
; #pragma unroll
;                     for (int bj = 0; bj < 2; ++bj) { GAS float* dd = d + cg0 + bj * 128; NT_ST((GAS f32x4*)dd, acc[ai][bj][m][0]); NT_ST((GAS f32x4*)(dd + 4), acc[ai][bj][m][1]); } } }
.Lep_done:
	s_mov_b32 s100, 1
	s_cmp_lt_u32 s74, 4
	s_cbranch_scc0 .LBB0_364
	v_or_b32_e32 v158, 16, v154
	v_or_b32_e32 v160, 32, v154
	v_or_b32_e32 v162, 48, v154
	v_add_u32_e32 v164, 0x80, v154
	v_add_u32_e32 v166, 0x90, v154
	v_add_u32_e32 v168, 0xa0, v154
	v_add_u32_e32 v170, 0xb0, v154
	s_movk_i32 s24, 0x4080
	v_cmp_gt_i32_e32 vcc, s24, v154
	s_xor_b64 s[24:25], s[36:37], -1
	s_and_b64 s[52:53], s[24:25], vcc
	v_mov_b64_e32 v[128:129], 0
	s_and_saveexec_b64 s[34:35], s[52:53]
	s_cbranch_execz .LBB0_305
	s_mov_b32 s52, 0xfe03f81
	v_mul_hi_i32 v128, v154, s52
	v_lshrrev_b32_e32 v129, 31, v128
	v_ashrrev_i32_e32 v128, 7, v128
	v_add_u32_e32 v131, v128, v129
	s_movk_i32 s52, 0xf7f0
	v_mad_i32_i24 v130, v131, s52, v154
	s_movk_i32 s52, 0x800
	v_cmp_lt_i32_e32 vcc, s52, v130
	v_mov_b64_e32 v[128:129], 0
	s_and_saveexec_b64 s[52:53], vcc
	s_cbranch_execz .LBB0_304
	v_readlane_b32 s62, v240, 35
	v_add_u32_e32 v172, 0xfffff7ff, v130
	s_nop 0
	v_add_u32_e32 v128, s62, v131
	v_mul_hi_i32_i24_e32 v129, 15, v128
	v_mul_i32_i24_e32 v128, 15, v128
	v_lshl_add_u64 v[128:129], v[128:129], 0, v[172:173]
	v_readlane_b32 s62, v240, 33
	v_lshlrev_b64 v[128:129], 12, v[128:129]
	v_readlane_b32 s63, v240, 34
	s_nop 1
	v_lshl_add_u64 v[128:129], s[62:63], 0, v[128:129]
